# attention tile loop: back-edge rotation (ring rotation, counters, issue flag before the end-of-tile wait/barrier), PV-block nop/duplicate-wait trims, on v28
# speedup vs baseline: 1.0030x; 1.0030x over previous
; __device__ __forceinline__ void att_qk_sm(const LAS unsigned char* kb, int klane, const bf16x8 (&qf)[12], f32x16 (&o)[4], float& mrun, float& lrun, bf16x8 (&pb)[4]) {
;     constexpr int KP = 400;
;     f32x16 s0, s1;
; #pragma unroll
;     for (int i = 0; i < 16; ++i) { s0[i] = 0.f; s1[i] = 0.f; }
;     bf16x8 ka[3][2];
; #pragma unroll
;     for (int g = 0; g < 2; ++g) { ka[g][0] = *(const LAS bf16x8*)(kb + klane + g * 32); ka[g][1] = *(const LAS bf16x8*)(kb + klane + 32 * KP + g * 32); }
; #pragma unroll
;     for (int g = 0; g < 12; ++g) {
;         if (g < 10) { ka[(g + 2) % 3][0] = *(const LAS bf16x8*)(kb + klane + (g + 2) * 32); ka[(g + 2) % 3][1] = *(const LAS bf16x8*)(kb + klane + 32 * KP + (g + 2) * 32); }
;         __builtin_amdgcn_sched_barrier(0);
;         s0 = __builtin_amdgcn_mfma_f32_32x32x16_bf16(ka[g % 3][0], qf[g], s0, 0, 0, 0);
;         s1 = __builtin_amdgcn_mfma_f32_32x32x16_bf16(ka[g % 3][1], qf[g], s1, 0, 0, 0);
;         __builtin_amdgcn_sched_barrier(0);
;     }
; __device__ __forceinline__ void att_pv(const LAS unsigned char* kb, int vlane, const bf16x8 (&pb)[4], f32x16 (&o)[4]) {
;     constexpr int VP = 320;
;     s16x4 vlo[2][4], vhi[2][4];
;     const unsigned vaddr = (unsigned)(unsigned long)(kb + vlane);
; #pragma unroll
;     for (int d = 0; d < 4; ++d) { TR_READ(vlo[0][d], vaddr, d * 64); TR_READ(vhi[0][d], vaddr, 8 * VP + d * 64); }
; #pragma unroll
;     for (int ks = 0; ks < 4; ++ks) {
;         if (ks < 3) {
; #pragma unroll
;             for (int d = 0; d < 4; ++d) { TR_READ(vlo[(ks + 1) & 1][d], vaddr, ((ks + 1) * 16) * VP + d * 64); TR_READ(vhi[(ks + 1) & 1][d], vaddr, ((ks + 1) * 16 + 8) * VP + d * 64); }
;             TR_WAIT4(8, vlo[ks & 1][0], vlo[ks & 1][1], vlo[ks & 1][2], vlo[ks & 1][3]); TR_WAIT4(8, vhi[ks & 1][0], vhi[ks & 1][1], vhi[ks & 1][2], vhi[ks & 1][3]);
;         } else {
;             TR_WAIT4(0, vlo[ks & 1][0], vlo[ks & 1][1], vlo[ks & 1][2], vlo[ks & 1][3]); TR_WAIT4(0, vhi[ks & 1][0], vhi[ks & 1][1], vhi[ks & 1][2], vhi[ks & 1][3]);
;         }
;         __builtin_amdgcn_sched_barrier(0);
; #pragma unroll
;         for (int d = 0; d < 4; ++d) { const bf16x8 a = __builtin_shufflevector(vlo[ks & 1][d], vhi[ks & 1][d], 0, 1, 2, 3, 4, 5, 6, 7);
;             o[d] = __builtin_amdgcn_mfma_f32_32x32x16_bf16(a, pb[ks], o[d], 0, 0, 0); }
;         __builtin_amdgcn_sched_barrier(0);
;     }
; }
.LBB0_1016:
	s_cmp_lg_u32 s16, 0
	s_cselect_b64 s[4:5], -1, 0
	s_and_b64 s[4:5], s[0:1], s[4:5]
	s_cmp_le_u32 s16, s51
	s_cselect_b64 s[62:63], -1, 0
	s_and_b64 s[4:5], s[4:5], s[62:63]
	s_andn2_b64 vcc, exec, s[4:5]
	s_cbranch_vccnz .LBB0_1018
	v_add_u32_e32 v80, s77, v222
	v_add_u32_e32 v186, 0x6400, v80
	ds_read_b64_tr_b16 v[80:81], v186 offset:0
	ds_read_b64_tr_b16 v[82:83], v186 offset:2560
	ds_read_b64_tr_b16 v[84:85], v186 offset:64
	ds_read_b64_tr_b16 v[86:87], v186 offset:2624
	ds_read_b64_tr_b16 v[88:89], v186 offset:128
	ds_read_b64_tr_b16 v[90:91], v186 offset:2688
	ds_read_b64_tr_b16 v[92:93], v186 offset:192
	ds_read_b64_tr_b16 v[94:95], v186 offset:2752
	ds_read_b64_tr_b16 v[170:171], v186 offset:5120
	ds_read_b64_tr_b16 v[172:173], v186 offset:7680
	ds_read_b64_tr_b16 v[174:175], v186 offset:5184
	ds_read_b64_tr_b16 v[176:177], v186 offset:7744
	ds_read_b64_tr_b16 v[178:179], v186 offset:5248
	ds_read_b64_tr_b16 v[180:181], v186 offset:7808
	ds_read_b64_tr_b16 v[182:183], v186 offset:5312
	ds_read_b64_tr_b16 v[184:185], v186 offset:7872
	s_waitcnt lgkmcnt(8)
	v_mfma_f32_32x32x16_bf16 v[48:63], v[80:83], v[76:79], v[48:63]
	v_mfma_f32_32x32x16_bf16 v[32:47], v[84:87], v[76:79], v[32:47]
	v_mfma_f32_32x32x16_bf16 v[16:31], v[88:91], v[76:79], v[16:31]
	v_mfma_f32_32x32x16_bf16 v[0:15], v[92:95], v[76:79], v[0:15]
	ds_read_b64_tr_b16 v[80:81], v186 offset:10240
	ds_read_b64_tr_b16 v[82:83], v186 offset:12800
	ds_read_b64_tr_b16 v[84:85], v186 offset:10304
	ds_read_b64_tr_b16 v[86:87], v186 offset:12864
	ds_read_b64_tr_b16 v[88:89], v186 offset:10368
	ds_read_b64_tr_b16 v[90:91], v186 offset:12928
	ds_read_b64_tr_b16 v[92:93], v186 offset:10432
	ds_read_b64_tr_b16 v[94:95], v186 offset:12992
	s_waitcnt lgkmcnt(8)
	v_mfma_f32_32x32x16_bf16 v[48:63], v[170:173], v[72:75], v[48:63]
	v_mfma_f32_32x32x16_bf16 v[32:47], v[174:177], v[72:75], v[32:47]
	v_mfma_f32_32x32x16_bf16 v[16:31], v[178:181], v[72:75], v[16:31]
	v_mfma_f32_32x32x16_bf16 v[0:15], v[182:185], v[72:75], v[0:15]
	ds_read_b64_tr_b16 v[170:171], v186 offset:15360
	ds_read_b64_tr_b16 v[172:173], v186 offset:17920
	ds_read_b64_tr_b16 v[174:175], v186 offset:15424
	ds_read_b64_tr_b16 v[176:177], v186 offset:17984
	ds_read_b64_tr_b16 v[178:179], v186 offset:15488
	ds_read_b64_tr_b16 v[180:181], v186 offset:18048
	ds_read_b64_tr_b16 v[182:183], v186 offset:15552
	ds_read_b64_tr_b16 v[184:185], v186 offset:18112
	s_waitcnt lgkmcnt(8)
	v_mfma_f32_32x32x16_bf16 v[48:63], v[80:83], v[68:71], v[48:63]
	v_mfma_f32_32x32x16_bf16 v[32:47], v[84:87], v[68:71], v[32:47]
	v_mfma_f32_32x32x16_bf16 v[16:31], v[88:91], v[68:71], v[16:31]
	v_mfma_f32_32x32x16_bf16 v[0:15], v[92:95], v[68:71], v[0:15]
	s_waitcnt lgkmcnt(0)
	v_mfma_f32_32x32x16_bf16 v[48:63], v[170:173], v[64:67], v[48:63]
	v_mfma_f32_32x32x16_bf16 v[32:47], v[174:177], v[64:67], v[32:47]
	v_mfma_f32_32x32x16_bf16 v[16:31], v[178:181], v[64:67], v[16:31]
	v_mfma_f32_32x32x16_bf16 v[0:15], v[182:185], v[64:67], v[0:15]
.LBB0_1018:
	s_cmp_gt_u32 s16, s6
	s_cselect_b64 s[16:17], -1, 0
	s_and_b64 vcc, exec, s[16:17]
	s_cbranch_vccnz .Latt_skipq
	v_add_u32_e32 v194, s74, v223
	ds_read_b128 v[64:67], v194
	ds_read_b128 v[68:71], v194 offset:12800
	ds_read_b128 v[170:173], v194 offset:32
	ds_read_b128 v[174:177], v194 offset:12832
	ds_read_b128 v[182:185], v194 offset:64
	ds_read_b128 v[178:181], v194 offset:12864
	s_waitcnt lgkmcnt(4)
	v_mfma_f32_32x32x16_bf16 v[80:95], v[64:67], v[96:99], 0
	v_mfma_f32_32x32x16_bf16 v[64:79], v[68:71], v[96:99], 0
	ds_read_b128 v[186:189], v194 offset:96
	ds_read_b128 v[190:193], v194 offset:12896
	s_waitcnt lgkmcnt(4)
	v_mfma_f32_32x32x16_bf16 v[80:95], v[170:173], v[100:103], v[80:95]
	v_mfma_f32_32x32x16_bf16 v[64:79], v[174:177], v[100:103], v[64:79]
	ds_read_b128 v[170:173], v194 offset:128
	ds_read_b128 v[174:177], v194 offset:12928
	s_waitcnt lgkmcnt(4)
	v_mfma_f32_32x32x16_bf16 v[80:95], v[182:185], v[104:107], v[80:95]
	v_mfma_f32_32x32x16_bf16 v[64:79], v[178:181], v[104:107], v[64:79]
	ds_read_b128 v[178:181], v194 offset:160
	ds_read_b128 v[182:185], v194 offset:12960
	s_waitcnt lgkmcnt(4)
	v_mfma_f32_32x32x16_bf16 v[80:95], v[186:189], v[108:111], v[80:95]
	v_mfma_f32_32x32x16_bf16 v[64:79], v[190:193], v[108:111], v[64:79]
	ds_read_b128 v[186:189], v194 offset:192
	ds_read_b128 v[190:193], v194 offset:12992
	s_waitcnt lgkmcnt(4)
	v_mfma_f32_32x32x16_bf16 v[80:95], v[170:173], v[112:115], v[80:95]
	v_mfma_f32_32x32x16_bf16 v[64:79], v[174:177], v[112:115], v[64:79]
	ds_read_b128 v[170:173], v194 offset:224
	ds_read_b128 v[174:177], v194 offset:13024
	s_waitcnt lgkmcnt(4)
	v_mfma_f32_32x32x16_bf16 v[80:95], v[178:181], v[116:119], v[80:95]
	v_mfma_f32_32x32x16_bf16 v[64:79], v[182:185], v[116:119], v[64:79]
	ds_read_b128 v[178:181], v194 offset:256
	ds_read_b128 v[182:185], v194 offset:13056
	s_waitcnt lgkmcnt(4)
	v_mfma_f32_32x32x16_bf16 v[80:95], v[186:189], v[120:123], v[80:95]
	v_mfma_f32_32x32x16_bf16 v[64:79], v[190:193], v[120:123], v[64:79]
	ds_read_b128 v[186:189], v194 offset:288
	ds_read_b128 v[190:193], v194 offset:13088
	s_waitcnt lgkmcnt(4)
	v_mfma_f32_32x32x16_bf16 v[80:95], v[170:173], v[124:127], v[80:95]
	v_mfma_f32_32x32x16_bf16 v[64:79], v[174:177], v[124:127], v[64:79]
	ds_read_b128 v[170:173], v194 offset:320
	ds_read_b128 v[174:177], v194 offset:13120
	s_waitcnt lgkmcnt(4)
	v_mfma_f32_32x32x16_bf16 v[80:95], v[178:181], v[128:131], v[80:95]
	v_mfma_f32_32x32x16_bf16 v[64:79], v[182:185], v[128:131], v[64:79]
	ds_read_b128 v[178:181], v194 offset:352
	ds_read_b128 v[182:185], v194 offset:13152
	s_waitcnt lgkmcnt(4)
	v_mfma_f32_32x32x16_bf16 v[80:95], v[186:189], v[132:135], v[80:95]
	v_mfma_f32_32x32x16_bf16 v[64:79], v[190:193], v[132:135], v[64:79]
	s_waitcnt lgkmcnt(2)
	v_mfma_f32_32x32x16_bf16 v[80:95], v[170:173], v[136:139], v[80:95]
	v_mfma_f32_32x32x16_bf16 v[64:79], v[174:177], v[136:139], v[64:79]
	s_waitcnt lgkmcnt(0)
	v_mfma_f32_32x32x16_bf16 v[80:95], v[178:181], v[140:143], v[80:95]
	v_mfma_f32_32x32x16_bf16 v[64:79], v[182:185], v[140:143], v[64:79]
	s_cmp_lg_u32 s83, 0
	s_cbranch_scc0 .Latt_noissue_q
	s_mov_b64 s[4:5], s[10:11]
	s_cmp_eq_u32 s33, 0
	s_cselect_b32 s82, s76, s80
	s_add_i32 m0, s76, s19
	v_lshl_add_u64 v[172:173], s[4:5], 0, v[144:145]
	global_load_lds_dwordx4 v[172:173], off
	s_add_i32 m0, s76, s20
	v_lshl_add_u64 v[172:173], s[4:5], 0, v[146:147]
	global_load_lds_dwordx4 v[172:173], off
	s_add_i32 m0, s76, s21
	v_lshl_add_u64 v[172:173], s[4:5], 0, v[148:149]
	global_load_lds_dwordx4 v[172:173], off
	s_add_i32 m0, s82, s22
	v_lshl_add_u64 v[172:173], s[4:5], 0, v[150:151]
	global_load_lds_dwordx4 v[172:173], off
	s_add_i32 m0, s80, s23
	v_lshl_add_u64 v[172:173], s[4:5], 0, v[156:157]
	global_load_lds_dwordx4 v[172:173], off
	s_add_i32 m0, s80, s24
	v_lshl_add_u64 v[172:173], s[4:5], 0, v[154:155]
	global_load_lds_dwordx4 v[172:173], off
	s_branch .Latt_issued_q

; #define ATT_ISSUE(tilebase, bufbase) do { const unsigned char* _tb = (tilebase); asm volatile("" : "+s"(_tb)); _Pragma("unroll") for (int _i = 0; _i < 6; ++_i) { int _q = wave + 8 * _i; _q = _q > 44 ? 44 : _q; \
;         __builtin_amdgcn_global_load_lds((const unsigned*)(_tb + goff[_i]), (LAS unsigned*)((bufbase) + _q * 1024), 16, 0, 0); } } while (0)
; #define ATT_BAR() do { asm volatile("s_waitcnt vmcnt(0) lgkmcnt(0)" ::: "memory"); __builtin_amdgcn_s_barrier(); asm volatile("" ::: "memory"); } while (0)
; __device__ __forceinline__ void att_mfma(const Params& P, LAS unsigned char* lds, int wave) {
;     ...
;         for (int kt = 0; kt < ntile; ++kt) {
;             if (kt + 1 < ntile) ATT_ISSUE(kvb + (size_t)(kt + 1) * 327680, lds + bnext * BUF);
;             if (!roleA && kt >= 1 && kt - 1 <= my_last) att_pv(lds + bprev * BUF, vlane, pb, o);
;             if (kt <= my_last) att_qk_sm(lds + bcur * BUF, klane, qf, o, mrun, lrun, pb);
;             if (roleA && kt <= my_last) att_pv(lds + bcur * BUF, vlane, pb, o);
;             ATT_BAR();
;             bprev = bcur; bcur = bnext; bnext = bnext == 2 ? 0 : bnext + 1;
;         }
.LBB0_1022:
	s_or_b64 s[4:5], s[0:1], s[16:17]
	s_and_b64 vcc, exec, s[4:5]
	s_cbranch_vccnz .LBB0_1024
	v_add_u32_e32 v80, s78, v222
	v_add_u32_e32 v186, 0x6400, v80
	ds_read_b64_tr_b16 v[80:81], v186 offset:0
	ds_read_b64_tr_b16 v[82:83], v186 offset:2560
	ds_read_b64_tr_b16 v[84:85], v186 offset:64
	ds_read_b64_tr_b16 v[86:87], v186 offset:2624
	ds_read_b64_tr_b16 v[88:89], v186 offset:128
	ds_read_b64_tr_b16 v[90:91], v186 offset:2688
	ds_read_b64_tr_b16 v[92:93], v186 offset:192
	ds_read_b64_tr_b16 v[94:95], v186 offset:2752
	ds_read_b64_tr_b16 v[170:171], v186 offset:5120
	ds_read_b64_tr_b16 v[172:173], v186 offset:7680
	ds_read_b64_tr_b16 v[174:175], v186 offset:5184
	ds_read_b64_tr_b16 v[176:177], v186 offset:7744
	ds_read_b64_tr_b16 v[178:179], v186 offset:5248
	ds_read_b64_tr_b16 v[180:181], v186 offset:7808
	ds_read_b64_tr_b16 v[182:183], v186 offset:5312
	ds_read_b64_tr_b16 v[184:185], v186 offset:7872
	s_waitcnt lgkmcnt(8)
	v_mfma_f32_32x32x16_bf16 v[48:63], v[80:83], v[76:79], v[48:63]
	v_mfma_f32_32x32x16_bf16 v[32:47], v[84:87], v[76:79], v[32:47]
	v_mfma_f32_32x32x16_bf16 v[16:31], v[88:91], v[76:79], v[16:31]
	v_mfma_f32_32x32x16_bf16 v[0:15], v[92:95], v[76:79], v[0:15]
	ds_read_b64_tr_b16 v[80:81], v186 offset:10240
	ds_read_b64_tr_b16 v[82:83], v186 offset:12800
	ds_read_b64_tr_b16 v[84:85], v186 offset:10304
	ds_read_b64_tr_b16 v[86:87], v186 offset:12864
	ds_read_b64_tr_b16 v[88:89], v186 offset:10368
	ds_read_b64_tr_b16 v[90:91], v186 offset:12928
	ds_read_b64_tr_b16 v[92:93], v186 offset:10432
	ds_read_b64_tr_b16 v[94:95], v186 offset:12992
	s_waitcnt lgkmcnt(8)
	v_mfma_f32_32x32x16_bf16 v[48:63], v[170:173], v[72:75], v[48:63]
	v_mfma_f32_32x32x16_bf16 v[32:47], v[174:177], v[72:75], v[32:47]
	v_mfma_f32_32x32x16_bf16 v[16:31], v[178:181], v[72:75], v[16:31]
	v_mfma_f32_32x32x16_bf16 v[0:15], v[182:185], v[72:75], v[0:15]
	ds_read_b64_tr_b16 v[170:171], v186 offset:15360
	ds_read_b64_tr_b16 v[172:173], v186 offset:17920
	ds_read_b64_tr_b16 v[174:175], v186 offset:15424
	ds_read_b64_tr_b16 v[176:177], v186 offset:17984
	ds_read_b64_tr_b16 v[178:179], v186 offset:15488
	ds_read_b64_tr_b16 v[180:181], v186 offset:18048
	ds_read_b64_tr_b16 v[182:183], v186 offset:15552
	ds_read_b64_tr_b16 v[184:185], v186 offset:18112
	s_waitcnt lgkmcnt(8)
	v_mfma_f32_32x32x16_bf16 v[48:63], v[80:83], v[68:71], v[48:63]
	v_mfma_f32_32x32x16_bf16 v[32:47], v[84:87], v[68:71], v[32:47]
	v_mfma_f32_32x32x16_bf16 v[16:31], v[88:91], v[68:71], v[16:31]
	v_mfma_f32_32x32x16_bf16 v[0:15], v[92:95], v[68:71], v[0:15]
	s_waitcnt lgkmcnt(0)
	v_mfma_f32_32x32x16_bf16 v[48:63], v[170:173], v[64:67], v[48:63]
	v_mfma_f32_32x32x16_bf16 v[32:47], v[174:177], v[64:67], v[32:47]
	v_mfma_f32_32x32x16_bf16 v[16:31], v[178:181], v[64:67], v[16:31]
	v_mfma_f32_32x32x16_bf16 v[0:15], v[182:185], v[64:67], v[0:15]
.LBB0_1024:
	s_add_u32 s10, s10, 0x50000
	s_addc_u32 s11, s11, 0
	s_mov_b32 s81, s74
	s_mov_b32 s74, s75
	s_mov_b32 s75, s76
	s_mov_b32 s76, s81
	s_mov_b32 s81, s77
	s_mov_b32 s77, s78
	s_mov_b32 s78, s79
	s_mov_b32 s79, s80
	s_mov_b32 s80, s81
	s_add_i32 s81, s60, 2
	s_cmp_lt_u32 s81, s50
	s_cselect_b32 s83, 1, 0
	s_mov_b32 s16, s60
	s_add_i32 s81, s60, 1
	s_add_i32 s60, s60, 1
	s_cmp_lt_u32 s81, s50
	s_cbranch_scc1 .Latt_wait6
	s_waitcnt vmcnt(0)
	s_branch .Latt_waitd

; #define ATT_BAR() do { asm volatile("s_waitcnt vmcnt(0) lgkmcnt(0)" ::: "memory"); __builtin_amdgcn_s_barrier(); asm volatile("" ::: "memory"); } while (0)
; __device__ __forceinline__ void att_mfma(const Params& P, LAS unsigned char* lds, int wave) {
;     ...
;             ATT_BAR();
;             bprev = bcur; bcur = bnext; bnext = bnext == 2 ? 0 : bnext + 1;
;         }
.Latt_waitd:
	s_cmp_eq_u32 s50, s16
	s_waitcnt lgkmcnt(0)
	s_barrier
	s_cbranch_scc0 .LBB0_1016
	s_branch .LBB0_1026

; #define LAS __attribute__((address_space(3)))
; #define TR_READ(dst, addr, off) asm volatile("ds_read_b64_tr_b16 %0, %1 offset:%c2" : "=v"(dst) : "v"(addr), "i"(off) : "memory")
; #define TR_WAIT4(n, a, b, c, d) asm volatile("s_waitcnt lgkmcnt(" #n ")" : "+v"(a), "+v"(b), "+v"(c), "+v"(d) :: "memory")
; __device__ __forceinline__ void att_pv(const LAS unsigned char* kb, int vlane, const bf16x8 (&pb)[4], f32x16 (&o)[4]) {
;     constexpr int VP = 320;
;     s16x4 vlo[2][4], vhi[2][4];
;     const unsigned vaddr = (unsigned)(unsigned long)(kb + vlane);
; #pragma unroll
;     for (int d = 0; d < 4; ++d) { TR_READ(vlo[0][d], vaddr, d * 64); TR_READ(vhi[0][d], vaddr, 8 * VP + d * 64); }
; #pragma unroll
;     for (int ks = 0; ks < 4; ++ks) {
;         if (ks < 3) {
; #pragma unroll
;             for (int d = 0; d < 4; ++d) { TR_READ(vlo[(ks + 1) & 1][d], vaddr, ((ks + 1) * 16) * VP + d * 64); TR_READ(vhi[(ks + 1) & 1][d], vaddr, ((ks + 1) * 16 + 8) * VP + d * 64); }
;             TR_WAIT4(8, vlo[ks & 1][0], vlo[ks & 1][1], vlo[ks & 1][2], vlo[ks & 1][3]); TR_WAIT4(8, vhi[ks & 1][0], vhi[ks & 1][1], vhi[ks & 1][2], vhi[ks & 1][3]);
;         } else {
;             TR_WAIT4(0, vlo[ks & 1][0], vlo[ks & 1][1], vlo[ks & 1][2], vlo[ks & 1][3]); TR_WAIT4(0, vhi[ks & 1][0], vhi[ks & 1][1], vhi[ks & 1][2], vhi[ks & 1][3]);
;         }
;         __builtin_amdgcn_sched_barrier(0);
; #pragma unroll
;         for (int d = 0; d < 4; ++d) { const bf16x8 a = __builtin_shufflevector(vlo[ks & 1][d], vhi[ks & 1][d], 0, 1, 2, 3, 4, 5, 6, 7);
;             o[d] = __builtin_amdgcn_mfma_f32_32x32x16_bf16(a, pb[ks], o[d], 0, 0, 0); }
;         __builtin_amdgcn_sched_barrier(0);
;     }
; }
; __device__ __forceinline__ void att_mfma(const Params& P, LAS unsigned char* lds, int wave) {
;     ...
;         if (!roleA && ntile - 1 <= my_last) att_pv(lds + bprev * BUF, vlane, pb, o);
.LBB0_1026:
	s_and_b64 vcc, exec, s[8:9]
	s_cbranch_vccz .LBB0_1007
	s_mul_i32 s4, s58, 0xb400
	v_add_u32_e32 v80, s77, v222
	v_add_u32_e32 v112, 0x6400, v80
	ds_read_b64_tr_b16 v[80:81], v112 offset:0
	ds_read_b64_tr_b16 v[82:83], v112 offset:2560
	ds_read_b64_tr_b16 v[84:85], v112 offset:64
	ds_read_b64_tr_b16 v[86:87], v112 offset:2624
	ds_read_b64_tr_b16 v[88:89], v112 offset:128
	ds_read_b64_tr_b16 v[90:91], v112 offset:2688
	ds_read_b64_tr_b16 v[92:93], v112 offset:192
	ds_read_b64_tr_b16 v[94:95], v112 offset:2752
	ds_read_b64_tr_b16 v[96:97], v112 offset:5120
	ds_read_b64_tr_b16 v[98:99], v112 offset:7680
	ds_read_b64_tr_b16 v[100:101], v112 offset:5184
	ds_read_b64_tr_b16 v[102:103], v112 offset:7744
	ds_read_b64_tr_b16 v[104:105], v112 offset:5248
	ds_read_b64_tr_b16 v[106:107], v112 offset:7808
	ds_read_b64_tr_b16 v[108:109], v112 offset:5312
	ds_read_b64_tr_b16 v[110:111], v112 offset:7872
	s_nop 0
	s_waitcnt lgkmcnt(8)
	s_waitcnt lgkmcnt(8)
	s_nop 0
	v_mfma_f32_32x32x16_bf16 v[48:63], v[80:83], v[76:79], v[48:63]
	v_mfma_f32_32x32x16_bf16 v[32:47], v[84:87], v[76:79], v[32:47]
	v_mfma_f32_32x32x16_bf16 v[16:31], v[88:91], v[76:79], v[16:31]
	v_mfma_f32_32x32x16_bf16 v[0:15], v[92:95], v[76:79], v[0:15]
	ds_read_b64_tr_b16 v[76:77], v112 offset:10240
	ds_read_b64_tr_b16 v[78:79], v112 offset:12800
	ds_read_b64_tr_b16 v[80:81], v112 offset:10304
	ds_read_b64_tr_b16 v[82:83], v112 offset:12864
	ds_read_b64_tr_b16 v[84:85], v112 offset:10368
	ds_read_b64_tr_b16 v[86:87], v112 offset:12928
	ds_read_b64_tr_b16 v[88:89], v112 offset:10432
	ds_read_b64_tr_b16 v[90:91], v112 offset:12992
	s_waitcnt lgkmcnt(8)
	s_waitcnt lgkmcnt(8)
	s_nop 0
	v_mfma_f32_32x32x16_bf16 v[48:63], v[96:99], v[72:75], v[48:63]
	v_mfma_f32_32x32x16_bf16 v[32:47], v[100:103], v[72:75], v[32:47]
	v_mfma_f32_32x32x16_bf16 v[16:31], v[104:107], v[72:75], v[16:31]
	v_mfma_f32_32x32x16_bf16 v[0:15], v[108:111], v[72:75], v[0:15]
	ds_read_b64_tr_b16 v[72:73], v112 offset:15360
	ds_read_b64_tr_b16 v[74:75], v112 offset:17920
	ds_read_b64_tr_b16 v[92:93], v112 offset:15424
	ds_read_b64_tr_b16 v[94:95], v112 offset:17984
	ds_read_b64_tr_b16 v[96:97], v112 offset:15488
	ds_read_b64_tr_b16 v[98:99], v112 offset:18048
	ds_read_b64_tr_b16 v[100:101], v112 offset:15552
	ds_read_b64_tr_b16 v[102:103], v112 offset:18112
	s_waitcnt lgkmcnt(8)
	s_waitcnt lgkmcnt(8)
	s_nop 0
	v_mfma_f32_32x32x16_bf16 v[48:63], v[76:79], v[68:71], v[48:63]
	v_mfma_f32_32x32x16_bf16 v[32:47], v[80:83], v[68:71], v[32:47]
	v_mfma_f32_32x32x16_bf16 v[16:31], v[84:87], v[68:71], v[16:31]
	v_mfma_f32_32x32x16_bf16 v[0:15], v[88:91], v[68:71], v[0:15]
	s_waitcnt lgkmcnt(0)
	s_waitcnt lgkmcnt(0)
	s_nop 0
	v_mfma_f32_32x32x16_bf16 v[48:63], v[72:75], v[64:67], v[48:63]
	v_mfma_f32_32x32x16_bf16 v[32:47], v[92:95], v[64:67], v[32:47]
	v_mfma_f32_32x32x16_bf16 v[16:31], v[96:99], v[64:67], v[16:31]
	v_mfma_f32_32x32x16_bf16 v[0:15], v[100:103], v[64:67], v[0:15]
	s_branch .LBB0_1007
